# idle-tail relocation of phase-0 weight/cache conversion and layer-1 adaLN vectors into the last-round idle workgroups of the SwiGLU / in-proj GEMM phases; resid epilogue loads up front, stores after l
# speedup vs baseline: 1.0891x; 1.0093x over previous
.LBB0_78:
	v_readlane_b32 s80, v255, 42
	v_readlane_b32 s84, v255, 44
	v_readlane_b32 s81, v255, 43
	v_readlane_b32 s85, v255, 45
	v_readlane_b32 s77, v255, 46
	v_readlane_b32 s76, v255, 47
	s_barrier
	v_readlane_b32 s0, v255, 48
	s_cmp_eq_u32 s0, 11
	s_cbranch_scc0 .Lp0t_n0_q10
	s_cmp_lt_u32 s34, 64
	s_cbranch_scc1 .Lp0t_n0_q10
	s_sub_i32 s45, s34, 64
	s_add_i32 s45, s45, 0x120
	s_mov_b32 s68, 0xc0
	s_mov_b32 s69, 0x39f
	s_mov_b32 s58, 0x240
	s_mov_b32 s59, 0x420
	s_mov_b32 s61, 0x7fffffff
	s_mov_b32 s74, 0x0
	s_mov_b32 s78, 0x7fffffff
	s_mov_b32 s79, 0x0
	s_mov_b32 s70, 0x0
	s_mov_b32 s71, 0x0
	s_cmp_gt_i32 s45, s69
	s_cbranch_scc1 .Lp0t_n0_q10
	s_branch .Lp0_tramp

.LBB0_430:
	v_readlane_b32 s84, v255, 44
	v_readlane_b32 s85, v255, 45
	v_readlane_b32 s77, v255, 46
	v_readlane_b32 s76, v255, 47
	s_barrier
	v_readlane_b32 s0, v255, 48
	s_cmp_eq_u32 s0, 5
	s_cbranch_scc0 .Lp0t_n0_q4a
	s_cmp_lt_u32 s34, 192
	s_cbranch_scc1 .Lp0t_n0_q4a
	s_sub_i32 s45, s34, 192
	s_add_i32 s45, s45, 0xb20
	s_mov_b32 s68, 0x40
	s_mov_b32 s69, 0xbff
	s_mov_b32 s58, 0x7fffffff
	s_mov_b32 s59, 0x0
	s_mov_b32 s61, 0x7fffffff
	s_mov_b32 s74, 0x0
	s_mov_b32 s78, 0x7fffffff
	s_mov_b32 s79, 0x0
	s_mov_b32 s70, 0x0
	s_mov_b32 s71, 0x0
	s_cmp_gt_i32 s45, s69
	s_cbranch_scc1 .Lp0t_n0_q4a
	s_branch .Lp0_full
.Lp0t_n0_q4a:
	s_cmp_eq_u32 s0, 17
	s_cbranch_scc0 .Lp0t_n1_q4a
	s_cmp_lt_u32 s34, 64
	s_cbranch_scc1 .Lp0t_n1_q4a
	s_sub_i32 s45, s34, 64
	s_add_i32 s45, s45, 0x9d0
	s_mov_b32 s68, 0xc0
	s_mov_b32 s69, 0xbbf
	s_mov_b32 s58, 0xa80
	s_mov_b32 s59, 0x200
	s_mov_b32 s61, 0xac0
	s_mov_b32 s74, 0x200
	s_mov_b32 s78, 0x7fffffff
	s_mov_b32 s79, 0x0
	s_mov_b32 s70, 0x0
	s_mov_b32 s71, 0x0
	s_cmp_gt_i32 s45, s69
	s_cbranch_scc1 .Lp0t_n1_q4a
	s_branch .Lp0_full
.Lp0t_n1_q4a:
.LBB0_431:
	s_mov_b64 s[0:1], 0
.LBB0_432:
	s_andn2_b64 vcc, exec, s[0:1]
	s_cbranch_vccnz .LBB0_452
	v_readlane_b32 s0, v252, 22
	v_mov_b32_e32 v1, v204
	v_readlane_b32 s1, v252, 23
	s_andn2_b64 vcc, exec, s[0:1]
	v_readfirstlane_b32 s3, v1
	s_cbranch_vccnz .LBB0_452
	v_lshlrev_b32_e32 v4, 4, v1
	v_add_u32_e32 v2, 0x2000, v4
	v_ashrrev_i32_e32 v0, 31, v2
	v_lshrrev_b32_e32 v0, 22, v0
	v_add_u32_e32 v0, v2, v0
	v_ashrrev_i32_e32 v0, 10, v0
	v_mul_i32_i24_e32 v3, 0x400, v0
	v_sub_u32_e32 v2, v2, v3
	v_lshrrev_b32_e32 v3, 4, v2
	v_bitop3_b32 v3, v3, v2, 32 bitop3:0x6c
	v_ashrrev_i32_e32 v2, 31, v3
	v_lshrrev_b32_e32 v2, 26, v2
	v_add_u32_e32 v5, v3, v2
	v_lshlrev_b32_e32 v6, 3, v0
	v_ashrrev_i32_e32 v2, 6, v5
	v_and_b32_e32 v6, -16, v6
	v_add_u32_e32 v6, v2, v6
	v_and_b32_e32 v7, 3, v2
	s_mov_b32 s1, 0x1fffe0
	v_lshrrev_b32_e32 v8, 2, v6
	v_lshlrev_b32_e32 v9, 1, v6
	v_and_b32_e32 v5, 0xc0, v5
	v_and_or_b32 v7, v6, s1, v7
	v_and_b32_e32 v8, 4, v8
	v_and_b32_e32 v9, 24, v9
	v_sub_u32_e32 v3, v3, v5
	v_mov_b32_e32 v11, 1
	v_or3_b32 v7, v7, v8, v9
	v_lshlrev_b32_e32 v8, 5, v0
	v_ashrrev_i16_sdwa v3, v11, sext(v3) dst_sel:DWORD dst_unused:UNUSED_PAD src0_sel:DWORD src1_sel:BYTE_0
	v_and_b32_e32 v8, 32, v8
	v_bfe_i32 v3, v3, 0, 16
	v_add_lshl_u32 v5, v8, v3, 1
	s_waitcnt vmcnt(0)
	v_lshl_add_u32 v130, v7, 11, v5
	v_lshl_add_u32 v132, v6, 11, v5
	v_bfe_i32 v5, v1, 27, 1
	v_lshrrev_b32_e32 v5, 22, v5
	v_add_u32_e32 v5, v4, v5
	v_and_b32_e32 v5, 0xfffffc00, v5
	v_sub_u32_e32 v4, v4, v5
	v_lshrrev_b32_e32 v5, 4, v4
	v_bitop3_b32 v6, v5, v4, 32 bitop3:0x6c
	v_ashrrev_i32_e32 v5, 31, v1
	v_lshrrev_b32_e32 v5, 26, v5
	v_ashrrev_i32_e32 v4, 31, v4
	v_add_u32_e32 v5, v1, v5
	v_lshrrev_b32_e32 v4, 26, v4
	v_ashrrev_i32_e32 v5, 6, v5
	v_add_u32_e32 v4, v6, v4
	v_lshlrev_b32_e32 v7, 3, v5
	v_ashrrev_i32_e32 v4, 6, v4
	v_and_b32_e32 v7, -16, v7
	v_add_u32_e32 v7, v4, v7
	v_and_b32_e32 v8, 3, v4
	v_lshrrev_b32_e32 v9, 2, v7
	v_lshlrev_b32_e32 v10, 1, v7
	v_and_or_b32 v8, v7, s1, v8
	v_and_b32_e32 v9, 4, v9
	v_and_b32_e32 v10, 24, v10
	v_or3_b32 v8, v8, v9, v10
	v_mul_i32_i24_e32 v10, 64, v4
	v_sub_u32_e32 v6, v6, v10
	s_ashr_i32 s0, s3, 6
	v_lshlrev_b32_e32 v9, 5, v5
	v_ashrrev_i16_sdwa v6, v11, sext(v6) dst_sel:DWORD dst_unused:UNUSED_PAD src0_sel:DWORD src1_sel:BYTE_0
	s_lshl_b32 s24, s0, 10
	v_and_b32_e32 v9, 32, v9
	v_bfe_i32 v6, v6, 0, 16
	v_add_lshl_u32 v9, v9, v6, 1
	s_add_i32 s36, s24, 0
	v_readlane_b32 s30, v252, 36
	v_lshl_add_u32 v96, v8, 11, v9
	s_add_i32 m0, s36, 0x10000
	v_readlane_b32 s31, v252, 37
	v_lshl_add_u32 v134, v7, 11, v9
	s_add_i32 s37, s36, 0x2000
	s_add_i32 s58, s36, 0x4000
	s_add_i32 s59, s36, 0x6000
	s_ashr_i32 s1, s3, 8
	global_load_lds_dwordx4 v96, s[30:31]
	s_add_i32 m0, s36, 0x12000
	s_nop 0
	global_load_lds_dwordx4 v130, s[30:31]
	v_readlane_b32 s30, v252, 32
	s_mov_b32 m0, s36
	v_readlane_b32 s31, v252, 33
	s_nop 4
	global_load_lds_dwordx4 v134, s[30:31]
	s_mov_b32 m0, s37
	s_nop 0
	global_load_lds_dwordx4 v132, s[30:31]
	v_readlane_b32 s30, v252, 30
	s_add_i32 m0, s36, 0x14000
	v_readlane_b32 s31, v252, 31
	s_nop 4
	global_load_lds_dwordx4 v96, s[30:31]
	s_add_i32 m0, s36, 0x16000
	s_cmp_lg_u32 s1, 1
	global_load_lds_dwordx4 v130, s[30:31]
	v_readlane_b32 s30, v252, 34
	s_mov_b32 m0, s58
	v_readlane_b32 s31, v252, 35
	s_nop 4
	global_load_lds_dwordx4 v134, s[30:31]
	s_mov_b32 m0, s59
	s_nop 0
	global_load_lds_dwordx4 v132, s[30:31]
	s_cbranch_scc1 .LBB0_436
	s_barrier

.LBB0_451:
	s_barrier
	v_readlane_b32 s0, v255, 48
	s_cmp_eq_u32 s0, 5
	s_cbranch_scc0 .Lp0t_n0_q4b
	s_cmp_lt_u32 s34, 192
	s_cbranch_scc1 .Lp0t_n0_q4b
	s_sub_i32 s45, s34, 192
	s_add_i32 s45, s45, 0xb20
	s_mov_b32 s68, 0x40
	s_mov_b32 s69, 0xbff
	s_mov_b32 s58, 0x7fffffff
	s_mov_b32 s59, 0x0
	s_mov_b32 s61, 0x7fffffff
	s_mov_b32 s74, 0x0
	s_mov_b32 s78, 0x7fffffff
	s_mov_b32 s79, 0x0
	s_mov_b32 s70, 0x0
	s_mov_b32 s71, 0x0
	s_cmp_gt_i32 s45, s69
	s_cbranch_scc1 .Lp0t_n0_q4b
	s_branch .Lp0_full

.Lp0t_n1_q4b:
.LBB0_452:
	s_mov_b64 s[0:1], 0
.LBB0_453:
	s_andn2_b64 vcc, exec, s[0:1]
	s_cbranch_vccnz .LBB0_462
	v_mov_b32_e32 v0, v204
	v_readlane_b32 s0, v254, 34
	v_ashrrev_i32_e32 v12, 6, v0
	s_waitcnt vmcnt(0)
	v_add_u32_e32 v143, s0, v12
	s_movk_i32 s0, 0x1800
	v_cmp_gt_i32_e32 vcc, s0, v143
	s_and_saveexec_b64 s[44:45], vcc
	s_cbranch_execz .LBB0_461
	v_lshlrev_b32_e32 v2, 2, v143
	v_ashrrev_i32_e32 v3, 31, v2
	v_lshlrev_b32_e32 v0, 2, v0
	v_lshlrev_b64 v[2:3], 12, v[2:3]
	v_and_b32_e32 v142, 0xfc, v0
	v_lshl_add_u64 v[2:3], s[90:91], 0, v[2:3]
	v_lshlrev_b32_e32 v96, 2, v142
	v_lshl_add_u64 v[14:15], v[2:3], 0, v[96:97]
	s_movk_i32 s0, 0x3000
	v_add_co_u32_e32 v4, vcc, s0, v14
	s_movk_i32 s0, 0x2000
	s_nop 0
	v_addc_co_u32_e32 v5, vcc, 0, v15, vcc
	v_add_co_u32_e32 v8, vcc, s0, v14
	s_movk_i32 s3, 0x1000
	s_nop 0
	v_addc_co_u32_e32 v9, vcc, 0, v15, vcc
	v_add_co_u32_e32 v20, vcc, s3, v14
	global_load_dwordx4 v[0:3], v[4:5], off offset:3072
	global_load_dwordx4 v[16:19], v[4:5], off offset:2048
	global_load_dwordx4 v[64:67], v[4:5], off offset:1024
	global_load_dwordx4 v[106:109], v[4:5], off
	v_addc_co_u32_e32 v21, vcc, 0, v15, vcc
	global_load_dwordx4 v[4:7], v[8:9], off offset:3072
	global_load_dwordx4 v[40:43], v[8:9], off offset:2048
	global_load_dwordx4 v[92:95], v[8:9], off offset:1024
	global_load_dwordx4 v[114:117], v[8:9], off
	s_nop 0
	global_load_dwordx4 v[8:11], v[20:21], off offset:3072
	global_load_dwordx4 v[80:83], v[20:21], off offset:2048
	global_load_dwordx4 v[110:113], v[20:21], off offset:1024
	global_load_dwordx4 v[122:125], v[20:21], off
	global_load_dwordx4 v[52:55], v[14:15], off offset:3072
	global_load_dwordx4 v[98:101], v[14:15], off offset:2048
	global_load_dwordx4 v[118:121], v[14:15], off offset:1024
	global_load_dwordx4 v[126:129], v[14:15], off
	v_and_b32_e32 v13, 64, v210
	v_add_u32_e32 v13, 64, v13
	v_xor_b32_e32 v14, 32, v210
	v_cmp_lt_i32_e32 vcc, v14, v13
	v_readlane_b32 s30, v255, 51
	v_readlane_b32 s31, v255, 52
	v_cndmask_b32_e32 v14, v210, v14, vcc
	v_lshlrev_b32_e32 v149, 2, v14
	v_xor_b32_e32 v14, 16, v210
	v_cmp_lt_i32_e32 vcc, v14, v13
	s_and_b64 s[0:1], s[30:31], exec
	v_readlane_b32 s4, v254, 58
	v_cndmask_b32_e32 v14, v210, v14, vcc
	v_lshlrev_b32_e32 v151, 2, v14
	v_xor_b32_e32 v14, 8, v210
	v_cmp_lt_i32_e32 vcc, v14, v13
	s_cselect_b32 s0, s3, 0x4000
	v_readlane_b32 s6, v254, 60
	v_cndmask_b32_e32 v14, v210, v14, vcc
	v_lshlrev_b32_e32 v153, 2, v14
	v_xor_b32_e32 v14, 4, v210
	v_cmp_lt_i32_e32 vcc, v14, v13
	v_readlane_b32 s7, v254, 61
	s_add_u32 s0, s6, s0
	v_cndmask_b32_e32 v14, v210, v14, vcc
	v_lshlrev_b32_e32 v159, 2, v14
	v_xor_b32_e32 v14, 2, v210
	v_cmp_lt_i32_e32 vcc, v14, v13
	s_addc_u32 s1, s7, 0
	s_and_b64 s[30:31], s[30:31], exec
	v_cndmask_b32_e32 v14, v210, v14, vcc
	v_lshlrev_b32_e32 v161, 2, v14
	v_xor_b32_e32 v14, 1, v210
	v_cmp_lt_i32_e32 vcc, v14, v13
	v_lshl_add_u64 v[144:145], s[0:1], 0, v[96:97]
	v_lshlrev_b32_e32 v96, 1, v142
	v_cndmask_b32_e32 v13, v210, v14, vcc
	v_readlane_b32 s0, v254, 24
	s_cselect_b32 s3, 0, 9
	v_lshlrev_b32_e32 v171, 2, v13
	v_lshl_add_u64 v[146:147], s[22:23], 0, v[96:97]
	v_or_b32_e32 v148, 0x100, v142
	v_or_b32_e32 v150, 0x200, v142
	v_or_b32_e32 v152, 0x300, v142
	v_lshl_add_u32 v154, v12, 2, s0
	s_mov_b64 s[30:31], 0
	v_readlane_b32 s5, v254, 59
	v_readlane_b32 s8, v254, 62
	v_readlane_b32 s9, v254, 63
	v_readlane_b32 s10, v255, 0
	v_readlane_b32 s11, v255, 1
	v_readlane_b32 s12, v255, 2
	v_readlane_b32 s13, v255, 3
	v_readlane_b32 s14, v255, 4
	v_readlane_b32 s15, v255, 5
	v_readlane_b32 s16, v255, 6
	v_readlane_b32 s17, v255, 7
	v_readlane_b32 s18, v255, 8
	v_readlane_b32 s19, v255, 9
	s_branch .LBB0_457

.LBB0_527:
	v_readlane_b32 s80, v255, 42
	v_readlane_b32 s84, v255, 44
	v_readlane_b32 s81, v255, 43
	v_readlane_b32 s85, v255, 45
	v_readlane_b32 s77, v255, 46
	v_readlane_b32 s76, v255, 47
	s_barrier
	v_readlane_b32 s0, v255, 48
	s_cmp_eq_u32 s0, 2
	s_cbranch_scc0 .Lp0t_n0_q1
	s_cmp_lt_u32 s34, 64
	s_cbranch_scc1 .Lp0t_n0_q1
	s_sub_i32 s45, s34, 64
	s_add_i32 s45, s45, 0x450
	s_mov_b32 s68, 0xc0
	s_mov_b32 s69, 0x95f
	s_mov_b32 s58, 0x660
	s_mov_b32 s59, 0x660
	s_mov_b32 s61, 0x860
	s_mov_b32 s74, 0x100
	s_mov_b32 s78, 0x7fffffff
	s_mov_b32 s79, 0x0
	s_mov_b32 s70, 0x0
	s_mov_b32 s71, 0x0
	s_cmp_gt_i32 s45, s69
	s_cbranch_scc1 .Lp0t_n0_q1
	s_branch .Lp0_full
.Lp0t_n0_q1:
	s_cmp_eq_u32 s0, 14
	s_cbranch_scc0 .Lp0t_n1_q1
	s_cmp_lt_u32 s34, 64
	s_cbranch_scc1 .Lp0t_n1_q1
	s_sub_i32 s45, s34, 64
	s_add_i32 s45, s45, 0x7c0
	s_mov_b32 s68, 0xc0
	s_mov_b32 s69, 0x9cf
	s_mov_b32 s58, 0x7fffffff
	s_mov_b32 s59, 0x0
	s_mov_b32 s61, 0x7fffffff
	s_mov_b32 s74, 0x0
	s_mov_b32 s78, 0x7fffffff
	s_mov_b32 s79, 0x0
	s_mov_b32 s70, 0x0
	s_mov_b32 s71, 0x0
	s_cmp_gt_i32 s45, s69
	s_cbranch_scc1 .Lp0t_n1_q1
	s_branch .Lp0_full

.LBB0_556:
	s_and_b64 vcc, exec, s[0:1]
	s_cbranch_vccz .LBB0_622
	s_mov_b32 s45, s34
	s_mov_b32 s68, s54
	s_mov_b32 s69, 0x44f
	s_mov_b32 s58, 0x120
	s_mov_b32 s59, 0x120
	s_mov_b32 s61, 0x330
	s_mov_b32 s74, 0x630
	s_mov_b32 s78, 0x3d0
	s_mov_b32 s79, 0xe0
	s_mov_b32 s70, 0x0
	s_mov_b32 s71, 0x0
.Lp0_full:
	v_mov_b32_e32 v0, v204
	s_movk_i32 s0, 0x800
	s_nop 0
	v_cmp_gt_i32_e32 vcc, s0, v0
	v_readlane_b32 s0, v252, 42
	v_readlane_b32 s1, v252, 43
	s_and_b64 s[30:31], s[0:1], vcc
	s_and_saveexec_b64 s[0:1], s[30:31]
	s_cbranch_execz .LBB0_565
	v_max_i32_e32 v1, 0x600, v0
	v_sub_u32_e32 v1, v1, v0
	v_add_u32_e32 v1, 0x1ff, v1
	s_movk_i32 s3, 0x1ff
	v_cmp_lt_u32_e32 vcc, s3, v1
	s_mov_b64 s[40:41], -1
	v_mov_b32_e32 v2, v0
	s_and_saveexec_b64 s[30:31], vcc
	s_cbranch_execz .LBB0_562
	v_lshrrev_b32_e32 v1, 9, v1
	v_add_u32_e32 v4, 1, v1
	v_and_b32_e32 v5, 0xfffffe, v4
	v_add_u32_e32 v1, 0x200, v0
	s_mov_b64 s[40:41], 0
	v_mov_b32_e32 v6, v5
	v_mov_b64_e32 v[2:3], v[0:1]

.LBB0_572:
	s_or_b64 exec, exec, s[0:1]
	v_readlane_b32 s0, v252, 44
	v_readlane_b32 s1, v252, 45
	s_andn2_b64 vcc, exec, s[0:1]
	s_waitcnt vmcnt(0) lgkmcnt(0)
	s_barrier
	s_cbranch_vccnz .LBB0_622
	v_lshlrev_b32_e32 v1, 3, v0
	v_and_b32_e32 v2, 0x1f8, v1
	v_readlane_b32 s0, v253, 63
	v_lshlrev_b32_e32 v96, 1, v2
	v_readlane_b32 s1, v254, 0
	v_and_b32_e32 v65, 56, v1
	v_readlane_b32 s4, v254, 58
	v_lshl_add_u64 v[42:43], s[0:1], 0, v[96:97]
	v_readlane_b32 s0, v251, 30
	v_lshlrev_b32_e32 v96, 1, v65
	v_readlane_b32 s1, v251, 31
	v_bfe_u32 v51, v1, 6, 3
	v_lshlrev_b32_e32 v1, 6, v0
	v_lshl_add_u64 v[44:45], s[0:1], 0, v[96:97]
	v_readlane_b32 s0, v251, 51
	v_readlane_b32 s1, v251, 52
	v_and_b32_e32 v48, 31, v0
	v_ashrrev_i32_e32 v50, 5, v0
	v_lshl_add_u64 v[46:47], s[0:1], 0, v[96:97]
	s_movk_i32 s0, 0x120
	v_cmp_gt_i32_e64 s[40:41], s0, v0
	s_movk_i32 s0, 0x480
	v_readlane_b32 s8, v254, 62
	v_readlane_b32 s9, v254, 63
	v_add_u32_e32 v49, 0xffe08000, v0
	v_add_u32_e32 v71, 0xffe28000, v0
	v_bfe_u32 v77, v0, 3, 2
	v_add_u32_e32 v79, 0xffe68000, v0
	v_bfe_u32 v81, v0, 4, 2
	v_and_b32_e32 v83, 0x200, v1
	v_lshlrev_b32_e32 v2, 6, v50
	v_lshl_add_u32 v3, v48, 2, 0
	v_mul_lo_u32 v4, v50, s0
	v_lshlrev_b32_e32 v5, 7, v50
	v_mov_b64_e32 v[0:1], s[8:9]
	s_mov_b32 s0, 0x9000
	v_lshl_add_u32 v88, v50, 8, 0
	v_mad_i64_i32 v[52:53], s[0:1], v2, s0, v[0:1]
	v_add_u32_e32 v89, v3, v4
	v_add_u32_e32 v90, v3, v5
	s_mov_b32 s3, s45
	s_cmp_lt_u32 s45, s58
	s_cbranch_scc1 .Lp0_map0
	s_add_i32 s3, s3, s59
	s_cmp_lt_u32 s45, s61
	s_cbranch_scc1 .Lp0_map0
	s_add_i32 s3, s3, s74
	s_cmp_lt_u32 s45, s78
	s_cbranch_scc1 .Lp0_map0
	s_add_i32 s3, s3, s79
.Lp0_map0:
	v_readlane_b32 s5, v254, 59
	v_readlane_b32 s6, v254, 60
	v_readlane_b32 s7, v254, 61
	v_readlane_b32 s10, v255, 0
	v_readlane_b32 s11, v255, 1
	v_readlane_b32 s12, v255, 2
	v_readlane_b32 s13, v255, 3
	v_readlane_b32 s14, v255, 4
	v_readlane_b32 s15, v255, 5
	v_readlane_b32 s16, v255, 6
	v_readlane_b32 s17, v255, 7
	v_readlane_b32 s18, v255, 8
	v_readlane_b32 s19, v255, 9
	s_branch .LBB0_576

.LBB0_575:
	s_add_i32 s45, s45, s68
	s_cmp_gt_i32 s45, s69
	s_cbranch_scc1 .LBB0_622
	s_mov_b32 s3, s45
	s_cmp_lt_u32 s45, s58
	s_cbranch_scc1 .Lp0_map1
	s_add_i32 s3, s3, s59
	s_cmp_lt_u32 s45, s61
	s_cbranch_scc1 .Lp0_map1
	s_add_i32 s3, s3, s74
	s_cmp_lt_u32 s45, s78
	s_cbranch_scc1 .Lp0_map1
	s_add_i32 s3, s3, s79
.Lp0_map1:
.LBB0_576:
	s_cmp_ge_u32 s45, s70
	s_cbranch_scc0 .Lp0_go
	s_cmp_lt_u32 s45, s71
	s_cbranch_scc1 .LBB0_575
